# phase C rotary epilogue: cos/sin chunks of blocks 1..7 requested in block 0, counted wait per block
# speedup vs baseline: 1.0023x; 1.0023x over previous
; __device__ __forceinline__ f32x4 mfma16(bf16x8 a, bf16x8 b, f32x4 c) { return __builtin_amdgcn_mfma_f32_16x16x32_bf16(a, b, c, 0, 0, 0); }
; #define WAIT_V(n) asm volatile("s_waitcnt vmcnt(" #n ")" ::: "memory")
; __device__ __forceinline__ void gemm_mainloop(f32x4 (&acc)[8][4], const GemmSrc& g, int K, char* lds) {
;     ...
;     for (int kt = 0; kt < KT; kt++) {
;         WAIT_V(0);
;         __builtin_amdgcn_s_barrier();
;         const char* st = lds + (kt & 1) * 65536;
;         bf16x8 afA[4], afB[4], bX[4], bY[4];
; #pragma unroll
;         for (int ni = 0; ni < 4; ni++) afA[ni] = *(const bf16x8*)(st + woff + ni * 16 * 128 + rdo0);
; #pragma unroll
;         for (int mi = 0; mi < 4; mi++) bX[mi] = *(const bf16x8*)(st + xoff + mi * 16 * 128 + rdo0);
;         if (kt + 1 < KT) gemm_issue(g, kt + 1, (kt + 1) & 1, lds);
; #pragma unroll
;         for (int mi = 0; mi < 4; mi++) bY[mi] = *(const bf16x8*)(st + xoff + (4 + mi) * 16 * 128 + rdo0);
; #pragma unroll
;         for (int ni = 0; ni < 4; ni++) afB[ni] = *(const bf16x8*)(st + woff + ni * 16 * 128 + rdo1);
; #pragma unroll
;         for (int mi = 0; mi < 4; mi++)
; #pragma unroll
;             for (int ni = 0; ni < 4; ni++) acc[mi][ni] = mfma16(afA[ni], bX[mi], acc[mi][ni]);
;         __builtin_amdgcn_sched_barrier(0);
; #pragma unroll
;         for (int mi = 0; mi < 4; mi++) bX[mi] = *(const bf16x8*)(st + xoff + mi * 16 * 128 + rdo1);
; #pragma unroll
;         for (int mi = 0; mi < 4; mi++)
; #pragma unroll
;             for (int ni = 0; ni < 4; ni++) acc[4 + mi][ni] = mfma16(afA[ni], bY[mi], acc[4 + mi][ni]);
;         __builtin_amdgcn_sched_barrier(0);
; #pragma unroll
;         for (int mi = 0; mi < 4; mi++) bY[mi] = *(const bf16x8*)(st + xoff + (4 + mi) * 16 * 128 + rdo1);
; #pragma unroll
;         for (int mi = 0; mi < 4; mi++)
; #pragma unroll
;             for (int ni = 0; ni < 4; ni++) acc[mi][ni] = mfma16(afB[ni], bX[mi], acc[mi][ni]);
;         __builtin_amdgcn_sched_barrier(0);
; #pragma unroll
;         for (int mi = 0; mi < 4; mi++)
; #pragma unroll
;             for (int ni = 0; ni < 4; ni++) acc[4 + mi][ni] = mfma16(afB[ni], bY[mi], acc[4 + mi][ni]);
.LBB0_300:
	s_add_i32 s45, s0, 0xffff0000
	s_and_b32 s45, s45, 0x10000
	v_or_b32_e32 v128, s45, v144
	v_add_u32_e32 v145, v128, v142
	s_waitcnt vmcnt(0)
	s_barrier
	ds_read_b128 v[146:149], v145 offset:32768
	ds_read_b128 v[160:163], v145 offset:34816
	ds_read_b128 v[164:167], v145 offset:36864
	ds_read_b128 v[168:171], v145 offset:38912
	v_add_u32_e32 v145, s45, v143
	v_add_u32_e32 v194, v145, v142
	ds_read_b128 v[172:175], v194
	ds_read_b128 v[176:179], v194 offset:2048
	ds_read_b128 v[180:183], v194 offset:4096
	ds_read_b128 v[184:187], v194 offset:6144
	s_waitcnt lgkmcnt(0)
	v_mfma_f32_16x16x32_bf16 v[124:127], v[146:149], v[172:175], v[124:127]
	v_mfma_f32_16x16x32_bf16 v[120:123], v[160:163], v[172:175], v[120:123]
	v_mfma_f32_16x16x32_bf16 v[116:119], v[164:167], v[172:175], v[116:119]
	v_add_u32_e32 v128, v128, v133
	v_mfma_f32_16x16x32_bf16 v[112:115], v[168:171], v[172:175], v[112:115]
	v_mfma_f32_16x16x32_bf16 v[108:111], v[146:149], v[176:179], v[108:111]
	v_mfma_f32_16x16x32_bf16 v[104:107], v[160:163], v[176:179], v[104:107]
	v_mfma_f32_16x16x32_bf16 v[100:103], v[164:167], v[176:179], v[100:103]
	v_mfma_f32_16x16x32_bf16 v[96:99], v[168:171], v[176:179], v[96:99]
	ds_read_b128 v[172:175], v194 offset:8192
	ds_read_b128 v[176:179], v194 offset:10240
	v_mfma_f32_16x16x32_bf16 v[92:95], v[146:149], v[180:183], v[92:95]
	v_mfma_f32_16x16x32_bf16 v[88:91], v[160:163], v[180:183], v[88:91]
	v_mfma_f32_16x16x32_bf16 v[84:87], v[164:167], v[180:183], v[84:87]
	v_mfma_f32_16x16x32_bf16 v[80:83], v[168:171], v[180:183], v[80:83]
	ds_read_b128 v[180:183], v194 offset:12288
	ds_read_b128 v[188:191], v194 offset:14336
	ds_read_b128 v[192:195], v128 offset:32768
	ds_read_b128 v[196:199], v128 offset:34816
	ds_read_b128 v[200:203], v128 offset:36864
	ds_read_b128 v[204:207], v128 offset:38912
	v_mfma_f32_16x16x32_bf16 v[76:79], v[146:149], v[184:187], v[76:79]
	v_mfma_f32_16x16x32_bf16 v[72:75], v[160:163], v[184:187], v[72:75]
	v_mfma_f32_16x16x32_bf16 v[68:71], v[164:167], v[184:187], v[68:71]
	v_mfma_f32_16x16x32_bf16 v[64:67], v[168:171], v[184:187], v[64:67]
	v_add_u32_e32 v128, v145, v133
	s_waitcnt lgkmcnt(0)
	v_mfma_f32_16x16x32_bf16 v[60:63], v[146:149], v[172:175], v[60:63]
	s_and_b32 s46, s0, 0x10000
	s_add_i32 s46, s46, s86
	v_lshl_add_u64 v[208:209], v[134:135], 0, s[8:9]
	s_mov_b32 m0, s46
	v_lshl_add_u64 v[216:217], v[208:209], 0, s[26:27]
	global_load_lds_dwordx4 v[216:217], off
	v_mfma_f32_16x16x32_bf16 v[56:59], v[160:163], v[172:175], v[56:59]
	v_mfma_f32_16x16x32_bf16 v[52:55], v[164:167], v[172:175], v[52:55]
	v_lshl_add_u64 v[210:211], v[136:137], 0, s[8:9]
	s_add_u32 m0, s46, 0x8000
	v_lshl_add_u64 v[218:219], v[210:211], 0, s[28:29]
	global_load_lds_dwordx4 v[218:219], off
	v_mfma_f32_16x16x32_bf16 v[48:51], v[168:171], v[172:175], v[48:51]
	v_mfma_f32_16x16x32_bf16 v[44:47], v[146:149], v[176:179], v[44:47]
	v_lshl_add_u64 v[212:213], v[138:139], 0, s[8:9]
	s_add_u32 m0, s46, 0x400
	v_lshl_add_u64 v[216:217], v[212:213], 0, s[30:31]
	global_load_lds_dwordx4 v[216:217], off
	v_mfma_f32_16x16x32_bf16 v[40:43], v[160:163], v[176:179], v[40:43]
	v_mfma_f32_16x16x32_bf16 v[36:39], v[164:167], v[176:179], v[36:39]
	v_lshl_add_u64 v[214:215], v[140:141], 0, s[8:9]
	s_add_u32 m0, s46, 0x8400
	v_lshl_add_u64 v[218:219], v[214:215], 0, s[34:35]
	global_load_lds_dwordx4 v[218:219], off
	v_mfma_f32_16x16x32_bf16 v[28:31], v[146:149], v[180:183], v[28:31]
	v_mfma_f32_16x16x32_bf16 v[24:27], v[160:163], v[180:183], v[24:27]
	s_add_u32 m0, s46, 0x800
	v_lshl_add_u64 v[216:217], v[208:209], 0, s[36:37]
	global_load_lds_dwordx4 v[216:217], off
	v_mfma_f32_16x16x32_bf16 v[20:23], v[164:167], v[180:183], v[20:23]
	v_mfma_f32_16x16x32_bf16 v[12:15], v[146:149], v[188:191], v[12:15]
	s_add_u32 m0, s46, 0x8800
	v_lshl_add_u64 v[218:219], v[210:211], 0, s[38:39]
	global_load_lds_dwordx4 v[218:219], off
	v_mfma_f32_16x16x32_bf16 v[8:11], v[160:163], v[188:191], v[8:11]
	v_mfma_f32_16x16x32_bf16 v[4:7], v[164:167], v[188:191], v[4:7]
	s_add_u32 m0, s46, 0xc00
	v_lshl_add_u64 v[216:217], v[212:213], 0, s[40:41]
	global_load_lds_dwordx4 v[216:217], off
	ds_read_b128 v[146:149], v128
	ds_read_b128 v[160:163], v128 offset:2048
	ds_read_b128 v[164:167], v128 offset:4096
	ds_read_b128 v[172:175], v128 offset:6144
	v_mfma_f32_16x16x32_bf16 v[32:35], v[168:171], v[176:179], v[32:35]
	v_mfma_f32_16x16x32_bf16 v[16:19], v[168:171], v[180:183], v[16:19]
	s_add_u32 m0, s46, 0x8c00
	v_lshl_add_u64 v[218:219], v[214:215], 0, s[42:43]
	global_load_lds_dwordx4 v[218:219], off
	v_mfma_f32_16x16x32_bf16 v[0:3], v[168:171], v[188:191], v[0:3]
	s_waitcnt lgkmcnt(0)
	v_mfma_f32_16x16x32_bf16 v[124:127], v[192:195], v[146:149], v[124:127]
	v_mfma_f32_16x16x32_bf16 v[120:123], v[196:199], v[146:149], v[120:123]
	v_mfma_f32_16x16x32_bf16 v[116:119], v[200:203], v[146:149], v[116:119]
	v_mfma_f32_16x16x32_bf16 v[112:115], v[204:207], v[146:149], v[112:115]
	v_mfma_f32_16x16x32_bf16 v[108:111], v[192:195], v[160:163], v[108:111]
	v_mfma_f32_16x16x32_bf16 v[104:107], v[196:199], v[160:163], v[104:107]
	v_mfma_f32_16x16x32_bf16 v[100:103], v[200:203], v[160:163], v[100:103]
	v_mfma_f32_16x16x32_bf16 v[96:99], v[204:207], v[160:163], v[96:99]
	v_mfma_f32_16x16x32_bf16 v[92:95], v[192:195], v[164:167], v[92:95]
	v_mfma_f32_16x16x32_bf16 v[88:91], v[196:199], v[164:167], v[88:91]
	v_mfma_f32_16x16x32_bf16 v[84:87], v[200:203], v[164:167], v[84:87]
	v_mfma_f32_16x16x32_bf16 v[80:83], v[204:207], v[164:167], v[80:83]
	ds_read_b128 v[146:149], v128 offset:8192
	ds_read_b128 v[160:163], v128 offset:10240
	ds_read_b128 v[164:167], v128 offset:12288
	ds_read_b128 v[168:171], v128 offset:14336
	v_mfma_f32_16x16x32_bf16 v[76:79], v[192:195], v[172:175], v[76:79]
	v_mfma_f32_16x16x32_bf16 v[72:75], v[196:199], v[172:175], v[72:75]
	v_mfma_f32_16x16x32_bf16 v[68:71], v[200:203], v[172:175], v[68:71]
	v_mfma_f32_16x16x32_bf16 v[64:67], v[204:207], v[172:175], v[64:67]
	s_waitcnt lgkmcnt(0)
; __device__ __forceinline__ f32x4 mfma16(bf16x8 a, bf16x8 b, f32x4 c) { return __builtin_amdgcn_mfma_f32_16x16x32_bf16(a, b, c, 0, 0, 0); }
; __device__ __forceinline__ void gemm_mainloop(f32x4 (&acc)[8][4], const GemmSrc& g, int K, char* lds) {
;     ...
;         for (int mi = 0; mi < 4; mi++) bX[mi] = *(const bf16x8*)(st + xoff + mi * 16 * 128 + rdo1);
; #pragma unroll
;         for (int mi = 0; mi < 4; mi++)
; #pragma unroll
;             for (int ni = 0; ni < 4; ni++) acc[4 + mi][ni] = mfma16(afA[ni], bY[mi], acc[4 + mi][ni]);
;         __builtin_amdgcn_sched_barrier(0);
; #pragma unroll
;         for (int mi = 0; mi < 4; mi++) bY[mi] = *(const bf16x8*)(st + xoff + (4 + mi) * 16 * 128 + rdo1);
; #pragma unroll
;         for (int mi = 0; mi < 4; mi++)
; #pragma unroll
;             for (int ni = 0; ni < 4; ni++) acc[mi][ni] = mfma16(afB[ni], bX[mi], acc[mi][ni]);
;         __builtin_amdgcn_sched_barrier(0);
; #pragma unroll
;         for (int mi = 0; mi < 4; mi++)
; #pragma unroll
;             for (int ni = 0; ni < 4; ni++) acc[4 + mi][ni] = mfma16(afB[ni], bY[mi], acc[4 + mi][ni]);
;         __builtin_amdgcn_sched_barrier(0);
;     }
	v_mfma_f32_16x16x32_bf16 v[60:63], v[192:195], v[146:149], v[60:63]
	v_mfma_f32_16x16x32_bf16 v[56:59], v[196:199], v[146:149], v[56:59]
	v_mfma_f32_16x16x32_bf16 v[52:55], v[200:203], v[146:149], v[52:55]
	v_mfma_f32_16x16x32_bf16 v[48:51], v[204:207], v[146:149], v[48:51]
	v_mfma_f32_16x16x32_bf16 v[44:47], v[192:195], v[160:163], v[44:47]
	v_mfma_f32_16x16x32_bf16 v[40:43], v[196:199], v[160:163], v[40:43]
	v_mfma_f32_16x16x32_bf16 v[36:39], v[200:203], v[160:163], v[36:39]
	v_mfma_f32_16x16x32_bf16 v[32:35], v[204:207], v[160:163], v[32:35]
	v_mfma_f32_16x16x32_bf16 v[28:31], v[192:195], v[164:167], v[28:31]
	v_mfma_f32_16x16x32_bf16 v[24:27], v[196:199], v[164:167], v[24:27]
	v_mfma_f32_16x16x32_bf16 v[20:23], v[200:203], v[164:167], v[20:23]
	v_mfma_f32_16x16x32_bf16 v[16:19], v[204:207], v[164:167], v[16:19]
	v_mfma_f32_16x16x32_bf16 v[12:15], v[192:195], v[168:171], v[12:15]
	v_mfma_f32_16x16x32_bf16 v[8:11], v[196:199], v[168:171], v[8:11]
	v_mfma_f32_16x16x32_bf16 v[4:7], v[200:203], v[168:171], v[4:7]
	v_mfma_f32_16x16x32_bf16 v[0:3], v[204:207], v[168:171], v[0:3]
	s_add_u32 s8, s8, 0x80
	s_addc_u32 s9, s9, 0
	s_add_i32 s0, s0, 0x10000
	s_cmpk_lg_i32 s8, 0x780
	s_cbranch_scc1 .LBB0_300
	v_or_b32_e32 v128, 0x8000, v144
	v_add_u32_e32 v151, 0x10000, v143
	v_add3_u32 v150, v128, v142, s52
	v_add_u32_e32 v192, v151, v142
	s_waitcnt vmcnt(0)
	s_barrier
	ds_read_b128 v[134:137], v150
	ds_read_b128 v[138:141], v150 offset:2048
	ds_read_b128 v[142:145], v192
	ds_read_b128 v[146:149], v192 offset:2048
	ds_read_b128 v[160:163], v150 offset:4096
	ds_read_b128 v[164:167], v150 offset:6144
	s_waitcnt lgkmcnt(0)
	v_mfma_f32_16x16x32_bf16 v[124:127], v[134:137], v[142:145], v[124:127]
	v_add3_u32 v128, v128, v133, s52
	v_mfma_f32_16x16x32_bf16 v[120:123], v[138:141], v[142:145], v[120:123]
	v_mfma_f32_16x16x32_bf16 v[116:119], v[160:163], v[142:145], v[116:119]
	v_mfma_f32_16x16x32_bf16 v[112:115], v[164:167], v[142:145], v[112:115]
	v_mfma_f32_16x16x32_bf16 v[108:111], v[134:137], v[146:149], v[108:111]
	v_mfma_f32_16x16x32_bf16 v[104:107], v[138:141], v[146:149], v[104:107]
	v_mfma_f32_16x16x32_bf16 v[100:103], v[160:163], v[146:149], v[100:103]
	v_mfma_f32_16x16x32_bf16 v[96:99], v[164:167], v[146:149], v[96:99]
	ds_read_b128 v[142:145], v192 offset:4096
	ds_read_b128 v[146:149], v192 offset:6144
	s_waitcnt lgkmcnt(0)
	v_mfma_f32_16x16x32_bf16 v[92:95], v[134:137], v[142:145], v[92:95]
	v_mfma_f32_16x16x32_bf16 v[88:91], v[138:141], v[142:145], v[88:91]
	v_mfma_f32_16x16x32_bf16 v[84:87], v[160:163], v[142:145], v[84:87]
	v_mfma_f32_16x16x32_bf16 v[80:83], v[164:167], v[142:145], v[80:83]
	ds_read_b128 v[142:145], v128 offset:6144
	ds_read_b128 v[168:171], v128 offset:4096
	ds_read_b128 v[172:175], v128 offset:2048
	ds_read_b128 v[176:179], v128
	ds_read_b128 v[180:183], v192 offset:14336
	ds_read_b128 v[184:187], v192 offset:12288
	ds_read_b128 v[188:191], v192 offset:10240
	ds_read_b128 v[192:195], v192 offset:8192
	v_mfma_f32_16x16x32_bf16 v[76:79], v[134:137], v[146:149], v[76:79]
	v_mfma_f32_16x16x32_bf16 v[72:75], v[138:141], v[146:149], v[72:75]
	v_mfma_f32_16x16x32_bf16 v[68:71], v[160:163], v[146:149], v[68:71]
	v_mfma_f32_16x16x32_bf16 v[64:67], v[164:167], v[146:149], v[64:67]
	v_add_u32_e32 v128, v151, v133
	s_waitcnt lgkmcnt(0)
	v_mfma_f32_16x16x32_bf16 v[60:63], v[134:137], v[192:195], v[60:63]
	v_mfma_f32_16x16x32_bf16 v[56:59], v[138:141], v[192:195], v[56:59]
	v_mfma_f32_16x16x32_bf16 v[52:55], v[160:163], v[192:195], v[52:55]
	v_mfma_f32_16x16x32_bf16 v[44:47], v[134:137], v[188:191], v[44:47]
	v_mfma_f32_16x16x32_bf16 v[40:43], v[138:141], v[188:191], v[40:43]
	v_mfma_f32_16x16x32_bf16 v[36:39], v[160:163], v[188:191], v[36:39]
	v_mfma_f32_16x16x32_bf16 v[28:31], v[134:137], v[184:187], v[28:31]
	v_mfma_f32_16x16x32_bf16 v[24:27], v[138:141], v[184:187], v[24:27]
	v_mfma_f32_16x16x32_bf16 v[20:23], v[160:163], v[184:187], v[20:23]
	v_mfma_f32_16x16x32_bf16 v[12:15], v[134:137], v[180:183], v[12:15]
	v_mfma_f32_16x16x32_bf16 v[8:11], v[138:141], v[180:183], v[8:11]
	v_mfma_f32_16x16x32_bf16 v[4:7], v[160:163], v[180:183], v[4:7]
	ds_read_b128 v[134:137], v128
	ds_read_b128 v[138:141], v128 offset:2048
	ds_read_b128 v[146:149], v128 offset:4096
	ds_read_b128 v[160:163], v128 offset:6144
	v_mfma_f32_16x16x32_bf16 v[48:51], v[164:167], v[192:195], v[48:51]
	v_mfma_f32_16x16x32_bf16 v[32:35], v[164:167], v[188:191], v[32:35]
	v_mfma_f32_16x16x32_bf16 v[16:19], v[164:167], v[184:187], v[16:19]
	v_mfma_f32_16x16x32_bf16 v[0:3], v[164:167], v[180:183], v[0:3]
	s_waitcnt lgkmcnt(0)
	v_mfma_f32_16x16x32_bf16 v[124:127], v[176:179], v[134:137], v[124:127]
	v_mfma_f32_16x16x32_bf16 v[120:123], v[172:175], v[134:137], v[120:123]
	v_mfma_f32_16x16x32_bf16 v[116:119], v[168:171], v[134:137], v[116:119]
	v_mfma_f32_16x16x32_bf16 v[112:115], v[142:145], v[134:137], v[112:115]
	v_mfma_f32_16x16x32_bf16 v[108:111], v[176:179], v[138:141], v[108:111]
	v_mfma_f32_16x16x32_bf16 v[104:107], v[172:175], v[138:141], v[104:107]
	v_mfma_f32_16x16x32_bf16 v[100:103], v[168:171], v[138:141], v[100:103]
	v_mfma_f32_16x16x32_bf16 v[96:99], v[142:145], v[138:141], v[96:99]
	v_mfma_f32_16x16x32_bf16 v[92:95], v[176:179], v[146:149], v[92:95]
	v_mfma_f32_16x16x32_bf16 v[88:91], v[172:175], v[146:149], v[88:91]
	v_mfma_f32_16x16x32_bf16 v[84:87], v[168:171], v[146:149], v[84:87]
	v_mfma_f32_16x16x32_bf16 v[80:83], v[142:145], v[146:149], v[80:83]
	ds_read_b128 v[134:137], v128 offset:8192
	ds_read_b128 v[138:141], v128 offset:10240
	ds_read_b128 v[146:149], v128 offset:12288
	ds_read_b128 v[164:167], v128 offset:14336
	v_mfma_f32_16x16x32_bf16 v[76:79], v[176:179], v[160:163], v[76:79]
	v_mfma_f32_16x16x32_bf16 v[72:75], v[172:175], v[160:163], v[72:75]
	v_mfma_f32_16x16x32_bf16 v[68:71], v[168:171], v[160:163], v[68:71]
	v_mfma_f32_16x16x32_bf16 v[64:67], v[142:145], v[160:163], v[64:67]
	s_waitcnt lgkmcnt(0)
; __device__ void phaseC(const Params& p, char* lds) {
;     ...
; #pragma unroll
;         for (int mi = 0; mi < 8; mi++) {
;             const int tok = m0 + wr * 128 + mi * 16 + r;
;             if (rope) {
;                 f32x4 v = acc[mi][0];
;                 f32x4 pr;
; #pragma unroll
;                 for (int j = 0; j < 4; j++) pr[j] = __shfl_xor(v[j], 32, 64);
;                 const int ib = (q & 1) * 4;
;                 const f32x4 k0 = *(const f32x4*)(cs + (size_t)tok * 16 + ib * 2);
;                 const f32x4 k1 = *(const f32x4*)(cs + (size_t)tok * 16 + ib * 2 + 4);
;                 const float cc[4] = {k0[0], k0[2], k1[0], k1[2]}, sn[4] = {k0[1], k0[3], k1[1], k1[3]};
; #pragma unroll
;                 for (int j = 0; j < 4; j++) v[j] = (q < 2) ? (v[j] * cc[j] - pr[j] * sn[j]) : (v[j] * cc[j] + pr[j] * sn[j]);
;                 acc[mi][0] = v;
;             }
	v_mfma_f32_16x16x32_bf16 v[60:63], v[176:179], v[134:137], v[60:63]
	v_mfma_f32_16x16x32_bf16 v[56:59], v[172:175], v[134:137], v[56:59]
	v_mfma_f32_16x16x32_bf16 v[52:55], v[168:171], v[134:137], v[52:55]
	v_mfma_f32_16x16x32_bf16 v[48:51], v[142:145], v[134:137], v[48:51]
	v_mfma_f32_16x16x32_bf16 v[44:47], v[176:179], v[138:141], v[44:47]
	v_mfma_f32_16x16x32_bf16 v[40:43], v[172:175], v[138:141], v[40:43]
	v_mfma_f32_16x16x32_bf16 v[36:39], v[168:171], v[138:141], v[36:39]
	v_mfma_f32_16x16x32_bf16 v[32:35], v[142:145], v[138:141], v[32:35]
	v_mfma_f32_16x16x32_bf16 v[28:31], v[176:179], v[146:149], v[28:31]
	v_mfma_f32_16x16x32_bf16 v[24:27], v[172:175], v[146:149], v[24:27]
	v_mfma_f32_16x16x32_bf16 v[20:23], v[168:171], v[146:149], v[20:23]
	v_mfma_f32_16x16x32_bf16 v[16:19], v[142:145], v[146:149], v[16:19]
	v_mfma_f32_16x16x32_bf16 v[12:15], v[176:179], v[164:167], v[12:15]
	v_mfma_f32_16x16x32_bf16 v[8:11], v[172:175], v[164:167], v[8:11]
	v_mfma_f32_16x16x32_bf16 v[4:7], v[168:171], v[164:167], v[4:7]
	v_mfma_f32_16x16x32_bf16 v[0:3], v[142:145], v[164:167], v[0:3]
	s_and_b32 s0, s75, 0xfffffc
	s_cmp_eq_u32 s0, 12
	s_cselect_b64 vcc, -1, 0
	s_add_i32 s0, s44, 0xfffff000
	s_cmpk_lt_u32 s0, 0x300
	s_cselect_b64 s[8:9], -1, 0
	s_and_b64 s[8:9], s[8:9], s[4:5]
	s_or_b64 s[46:47], vcc, s[8:9]
	v_add_u32_e32 v136, s82, v153
	s_waitcnt vmcnt(0)
	s_barrier
	s_and_saveexec_b64 s[48:49], s[46:47]
	s_cbranch_execz .LBB0_303
	v_ashrrev_i32_e32 v137, 31, v136
	v_lshlrev_b64 v[134:135], 6, v[136:137]
	v_lshl_add_u64 v[134:135], v[130:131], 0, v[134:135]
	global_load_dwordx4 v[138:141], v[134:135], off
	global_load_dwordx4 v[142:145], v[134:135], off offset:16
	v_or_b32_e32 v216, 16, v136
	v_ashrrev_i32_e32 v217, 31, v216
	v_lshlrev_b64 v[216:217], 6, v[216:217]
	v_lshl_add_u64 v[216:217], v[130:131], 0, v[216:217]
	global_load_dwordx4 v[184:187], v[216:217], off
	global_load_dwordx4 v[188:191], v[216:217], off offset:16
	v_or_b32_e32 v218, 32, v136
	v_ashrrev_i32_e32 v219, 31, v218
	v_lshlrev_b64 v[218:219], 6, v[218:219]
	v_lshl_add_u64 v[218:219], v[130:131], 0, v[218:219]
	global_load_dwordx4 v[192:195], v[218:219], off
	global_load_dwordx4 v[196:199], v[218:219], off offset:16
	v_or_b32_e32 v220, 48, v136
	v_ashrrev_i32_e32 v221, 31, v220
	v_lshlrev_b64 v[220:221], 6, v[220:221]
	v_lshl_add_u64 v[220:221], v[130:131], 0, v[220:221]
	global_load_dwordx4 v[200:203], v[220:221], off
	global_load_dwordx4 v[204:207], v[220:221], off offset:16
	v_or_b32_e32 v216, 64, v136
	v_ashrrev_i32_e32 v217, 31, v216
	v_lshlrev_b64 v[216:217], 6, v[216:217]
	v_lshl_add_u64 v[216:217], v[130:131], 0, v[216:217]
	global_load_dwordx4 v[208:211], v[216:217], off
	global_load_dwordx4 v[212:215], v[216:217], off offset:16
	v_or_b32_e32 v218, 0x50, v136
	v_ashrrev_i32_e32 v219, 31, v218
	v_lshlrev_b64 v[218:219], 6, v[218:219]
	v_lshl_add_u64 v[218:219], v[130:131], 0, v[218:219]
	global_load_dwordx4 v[224:227], v[218:219], off
	global_load_dwordx4 v[228:231], v[218:219], off offset:16
	v_or_b32_e32 v220, 0x60, v136
	v_ashrrev_i32_e32 v221, 31, v220
	v_lshlrev_b64 v[220:221], 6, v[220:221]
	v_lshl_add_u64 v[220:221], v[130:131], 0, v[220:221]
	global_load_dwordx4 v[232:235], v[220:221], off
	global_load_dwordx4 v[236:239], v[220:221], off offset:16
	v_or_b32_e32 v216, 0x70, v136
	v_ashrrev_i32_e32 v217, 31, v216
	v_lshlrev_b64 v[216:217], 6, v[216:217]
	v_lshl_add_u64 v[216:217], v[130:131], 0, v[216:217]
	global_load_dwordx4 v[240:243], v[216:217], off
	global_load_dwordx4 v[244:247], v[216:217], off offset:16
	v_and_b32_e32 v133, 64, v159
	v_xor_b32_e32 v128, 32, v159
	v_add_u32_e32 v133, 64, v133
	v_cmp_lt_i32_e64 s[8:9], v128, v133
	s_waitcnt vmcnt(15)
	v_mov_b32_e32 v149, v140
	v_cndmask_b32_e64 v128, v159, v128, s[8:9]
	v_lshlrev_b32_e32 v128, 2, v128
	ds_bpermute_b32 v134, v128, v124
	ds_bpermute_b32 v135, v128, v125
	ds_bpermute_b32 v146, v128, v126
	ds_bpermute_b32 v147, v128, v127
	v_mov_b32_e32 v140, v139
	s_waitcnt vmcnt(14)
	v_mov_b32_e32 v139, v144
	v_mov_b32_e32 v144, v143
	s_waitcnt lgkmcnt(2)
	v_pk_mul_f32 v[134:135], v[140:141], v[134:135]
	s_waitcnt lgkmcnt(0)
	v_pk_mul_f32 v[140:141], v[144:145], v[146:147]
	v_mov_b32_e32 v148, v138
	v_mov_b32_e32 v138, v142
	v_cndmask_b32_e64 v135, v135, -v135, s[6:7]
	v_cndmask_b32_e64 v134, v134, -v134, s[6:7]
	v_cndmask_b32_e64 v141, v141, -v141, s[6:7]
	v_cndmask_b32_e64 v140, v140, -v140, s[6:7]
	v_pk_fma_f32 v[124:125], v[124:125], v[148:149], v[134:135]
	v_pk_fma_f32 v[126:127], v[126:127], v[138:139], v[140:141]
; __device__ void phaseC(const Params& p, char* lds) {
;     ...
; #pragma unroll
;         for (int mi = 0; mi < 8; mi++) {
;             const int tok = m0 + wr * 128 + mi * 16 + r;
;             if (rope) {
;                 f32x4 v = acc[mi][0];
;                 f32x4 pr;
; #pragma unroll
;                 for (int j = 0; j < 4; j++) pr[j] = __shfl_xor(v[j], 32, 64);
;                 const int ib = (q & 1) * 4;
;                 const f32x4 k0 = *(const f32x4*)(cs + (size_t)tok * 16 + ib * 2);
;                 const f32x4 k1 = *(const f32x4*)(cs + (size_t)tok * 16 + ib * 2 + 4);
;                 const float cc[4] = {k0[0], k0[2], k1[0], k1[2]}, sn[4] = {k0[1], k0[3], k1[1], k1[3]};
; #pragma unroll
;                 for (int j = 0; j < 4; j++) v[j] = (q < 2) ? (v[j] * cc[j] - pr[j] * sn[j]) : (v[j] * cc[j] + pr[j] * sn[j]);
;                 acc[mi][0] = v;
;             }
; #pragma unroll
;             for (int ni = 0; ni < 4; ni++) epi_fill(lds, wr, wc, r, q, mi, ni, acc[mi][ni] * scl);
.LBB0_303:
	s_or_b64 exec, exec, s[48:49]
	v_cndmask_b32_e32 v134, 1.0, v155, vcc
	v_pk_mul_f32 v[138:139], v[134:135], v[126:127] op_sel_hi:[0,1]
	v_pk_mul_f32 v[140:141], v[134:135], v[124:125] op_sel_hi:[0,1]
	v_cvt_pk_bf16_f32 v140, v140, v141
	v_cvt_pk_bf16_f32 v141, v138, v139
	v_pk_mul_f32 v[138:139], v[134:135], v[122:123] op_sel_hi:[0,1]
	v_pk_mul_f32 v[142:143], v[134:135], v[120:121] op_sel_hi:[0,1]
	v_cvt_pk_bf16_f32 v142, v142, v143
	v_cvt_pk_bf16_f32 v143, v138, v139
	ds_write2_b64 v156, v[140:141], v[142:143] offset1:4
	v_pk_mul_f32 v[138:139], v[134:135], v[118:119] op_sel_hi:[0,1]
	v_pk_mul_f32 v[140:141], v[134:135], v[116:117] op_sel_hi:[0,1]
	v_cvt_pk_bf16_f32 v140, v140, v141
	v_cvt_pk_bf16_f32 v141, v138, v139
	v_pk_mul_f32 v[138:139], v[134:135], v[114:115] op_sel_hi:[0,1]
	v_pk_mul_f32 v[142:143], v[134:135], v[112:113] op_sel_hi:[0,1]
	v_cvt_pk_bf16_f32 v142, v142, v143
	v_cvt_pk_bf16_f32 v143, v138, v139
	ds_write2_b64 v156, v[140:141], v[142:143] offset0:8 offset1:12
	s_and_saveexec_b64 s[8:9], s[46:47]
	s_cbranch_execz .LBB0_305
	v_or_b32_e32 v138, 16, v136
	v_ashrrev_i32_e32 v139, 31, v138
	v_lshlrev_b64 v[138:139], 6, v[138:139]
	v_lshl_add_u64 v[142:143], v[130:131], 0, v[138:139]
	s_nop 0
	v_and_b32_e32 v133, 64, v159
	v_xor_b32_e32 v128, 32, v159
	v_add_u32_e32 v133, 64, v133
	v_cmp_lt_i32_e32 vcc, v128, v133
	s_waitcnt vmcnt(13)
	v_mov_b32_e32 v138, v184
	v_mov_b32_e32 v139, v185
	v_mov_b32_e32 v140, v186
	v_mov_b32_e32 v141, v187
	v_mov_b32_e32 v151, v140
	v_cndmask_b32_e32 v128, v159, v128, vcc
	v_lshlrev_b32_e32 v128, 2, v128
	ds_bpermute_b32 v146, v128, v108
	ds_bpermute_b32 v147, v128, v109
	ds_bpermute_b32 v148, v128, v110
	ds_bpermute_b32 v149, v128, v111
	v_mov_b32_e32 v140, v139
	s_waitcnt vmcnt(12)
	v_mov_b32_e32 v142, v188
	v_mov_b32_e32 v143, v189
	v_mov_b32_e32 v144, v190
	v_mov_b32_e32 v145, v191
	v_mov_b32_e32 v139, v144
	v_mov_b32_e32 v144, v143
	v_mov_b32_e32 v150, v138
	v_mov_b32_e32 v138, v142
	s_waitcnt lgkmcnt(2)
	v_pk_mul_f32 v[140:141], v[140:141], v[146:147]
	s_waitcnt lgkmcnt(0)
	v_pk_mul_f32 v[142:143], v[144:145], v[148:149]
	v_cndmask_b32_e64 v141, v141, -v141, s[6:7]
	v_cndmask_b32_e64 v140, v140, -v140, s[6:7]
	v_cndmask_b32_e64 v143, v143, -v143, s[6:7]
	v_cndmask_b32_e64 v142, v142, -v142, s[6:7]
	v_pk_fma_f32 v[108:109], v[108:109], v[150:151], v[140:141]
	v_pk_fma_f32 v[110:111], v[110:111], v[138:139], v[142:143]
.LBB0_305:
	s_or_b64 exec, exec, s[8:9]
	v_mov_b32_e32 v135, v134
	v_mov_b32_e32 v138, v134
	v_mov_b32_e32 v139, v134
	v_pk_mul_f32 v[140:141], v[138:139], v[110:111]
	v_pk_mul_f32 v[142:143], v[134:135], v[108:109]
	v_pk_mul_f32 v[144:145], v[134:135], v[104:105]
	v_cvt_pk_bf16_f32 v142, v142, v143
	v_cvt_pk_bf16_f32 v143, v140, v141
	v_pk_mul_f32 v[140:141], v[138:139], v[106:107]
	v_cvt_pk_bf16_f32 v144, v144, v145
	v_cvt_pk_bf16_f32 v145, v140, v141
	v_add_u32_e32 v128, 0x2000, v156
	ds_write2_b64 v128, v[142:143], v[144:145] offset0:32 offset1:36
	v_pk_mul_f32 v[140:141], v[138:139], v[102:103]
	v_pk_mul_f32 v[142:143], v[134:135], v[100:101]
	v_pk_mul_f32 v[144:145], v[134:135], v[96:97]
	v_cvt_pk_bf16_f32 v142, v142, v143
	v_cvt_pk_bf16_f32 v143, v140, v141
	v_pk_mul_f32 v[140:141], v[138:139], v[98:99]
	v_cvt_pk_bf16_f32 v144, v144, v145
	v_cvt_pk_bf16_f32 v145, v140, v141
	ds_write2_b64 v128, v[142:143], v[144:145] offset0:40 offset1:44
	s_and_saveexec_b64 s[8:9], s[46:47]
	s_cbranch_execz .LBB0_307
	v_or_b32_e32 v140, 32, v136
	v_ashrrev_i32_e32 v141, 31, v140
	v_lshlrev_b64 v[140:141], 6, v[140:141]
	v_lshl_add_u64 v[144:145], v[130:131], 0, v[140:141]
	s_nop 0
	v_and_b32_e32 v133, 64, v159
	v_xor_b32_e32 v128, 32, v159
	v_add_u32_e32 v133, 64, v133
	v_cmp_lt_i32_e32 vcc, v128, v133
	s_waitcnt vmcnt(11)
	v_mov_b32_e32 v140, v192
	v_mov_b32_e32 v141, v193
	v_mov_b32_e32 v142, v194
	v_mov_b32_e32 v143, v195
	v_mov_b32_e32 v161, v142
	v_cndmask_b32_e32 v128, v159, v128, vcc
	v_lshlrev_b32_e32 v128, 2, v128
	ds_bpermute_b32 v148, v128, v92
	ds_bpermute_b32 v149, v128, v93
	ds_bpermute_b32 v150, v128, v94
	ds_bpermute_b32 v151, v128, v95
	v_mov_b32_e32 v142, v141
	s_waitcnt vmcnt(10)
	v_mov_b32_e32 v144, v196
	v_mov_b32_e32 v145, v197
	v_mov_b32_e32 v146, v198
	v_mov_b32_e32 v147, v199
	v_mov_b32_e32 v141, v146
	v_mov_b32_e32 v146, v145
	v_mov_b32_e32 v160, v140
	v_mov_b32_e32 v140, v144
	s_waitcnt lgkmcnt(2)
	v_pk_mul_f32 v[142:143], v[142:143], v[148:149]
	s_waitcnt lgkmcnt(0)
	v_pk_mul_f32 v[144:145], v[146:147], v[150:151]
	v_cndmask_b32_e64 v143, v143, -v143, s[6:7]
	v_cndmask_b32_e64 v142, v142, -v142, s[6:7]
	v_cndmask_b32_e64 v145, v145, -v145, s[6:7]
	v_cndmask_b32_e64 v144, v144, -v144, s[6:7]
	v_pk_fma_f32 v[92:93], v[92:93], v[160:161], v[142:143]
	v_pk_fma_f32 v[94:95], v[94:95], v[140:141], v[144:145]
; __device__ void phaseC(const Params& p, char* lds) {
;     ...
; #pragma unroll
;         for (int mi = 0; mi < 8; mi++) {
;             const int tok = m0 + wr * 128 + mi * 16 + r;
;             if (rope) {
;                 f32x4 v = acc[mi][0];
;                 f32x4 pr;
; #pragma unroll
;                 for (int j = 0; j < 4; j++) pr[j] = __shfl_xor(v[j], 32, 64);
;                 const int ib = (q & 1) * 4;
;                 const f32x4 k0 = *(const f32x4*)(cs + (size_t)tok * 16 + ib * 2);
;                 const f32x4 k1 = *(const f32x4*)(cs + (size_t)tok * 16 + ib * 2 + 4);
;                 const float cc[4] = {k0[0], k0[2], k1[0], k1[2]}, sn[4] = {k0[1], k0[3], k1[1], k1[3]};
; #pragma unroll
;                 for (int j = 0; j < 4; j++) v[j] = (q < 2) ? (v[j] * cc[j] - pr[j] * sn[j]) : (v[j] * cc[j] + pr[j] * sn[j]);
;                 acc[mi][0] = v;
;             }
; #pragma unroll
;             for (int ni = 0; ni < 4; ni++) epi_fill(lds, wr, wc, r, q, mi, ni, acc[mi][ni] * scl);
.LBB0_307:
	s_or_b64 exec, exec, s[8:9]
	v_pk_mul_f32 v[140:141], v[138:139], v[94:95]
	v_pk_mul_f32 v[142:143], v[134:135], v[92:93]
	v_pk_mul_f32 v[144:145], v[134:135], v[88:89]
	v_cvt_pk_bf16_f32 v142, v142, v143
	v_cvt_pk_bf16_f32 v143, v140, v141
	v_pk_mul_f32 v[140:141], v[138:139], v[90:91]
	v_cvt_pk_bf16_f32 v144, v144, v145
	v_cvt_pk_bf16_f32 v145, v140, v141
	v_add_u32_e32 v128, 0x4000, v156
	ds_write2_b64 v128, v[142:143], v[144:145] offset0:64 offset1:68
	v_pk_mul_f32 v[140:141], v[138:139], v[86:87]
	v_pk_mul_f32 v[142:143], v[134:135], v[84:85]
	v_pk_mul_f32 v[138:139], v[138:139], v[82:83]
	v_cvt_pk_bf16_f32 v142, v142, v143
	v_cvt_pk_bf16_f32 v143, v140, v141
	v_pk_mul_f32 v[140:141], v[134:135], v[80:81]
	s_nop 0
	v_cvt_pk_bf16_f32 v140, v140, v141
	v_cvt_pk_bf16_f32 v141, v138, v139
	ds_write2_b64 v128, v[142:143], v[140:141] offset0:72 offset1:76
	s_and_saveexec_b64 s[8:9], s[46:47]
	s_cbranch_execz .LBB0_309
	v_or_b32_e32 v138, 48, v136
	v_ashrrev_i32_e32 v139, 31, v138
	v_lshlrev_b64 v[138:139], 6, v[138:139]
	v_lshl_add_u64 v[142:143], v[130:131], 0, v[138:139]
	s_nop 0
	v_and_b32_e32 v133, 64, v159
	v_xor_b32_e32 v128, 32, v159
	v_add_u32_e32 v133, 64, v133
	v_cmp_lt_i32_e32 vcc, v128, v133
	s_waitcnt vmcnt(9)
	v_mov_b32_e32 v138, v200
	v_mov_b32_e32 v139, v201
	v_mov_b32_e32 v140, v202
	v_mov_b32_e32 v141, v203
	v_mov_b32_e32 v151, v140
	v_cndmask_b32_e32 v128, v159, v128, vcc
	v_lshlrev_b32_e32 v128, 2, v128
	ds_bpermute_b32 v146, v128, v76
	ds_bpermute_b32 v147, v128, v77
	ds_bpermute_b32 v148, v128, v78
	ds_bpermute_b32 v149, v128, v79
	v_mov_b32_e32 v140, v139
	s_waitcnt vmcnt(8)
	v_mov_b32_e32 v142, v204
	v_mov_b32_e32 v143, v205
	v_mov_b32_e32 v144, v206
	v_mov_b32_e32 v145, v207
	v_mov_b32_e32 v139, v144
	v_mov_b32_e32 v144, v143
	v_mov_b32_e32 v150, v138
	v_mov_b32_e32 v138, v142
	s_waitcnt lgkmcnt(2)
	v_pk_mul_f32 v[140:141], v[140:141], v[146:147]
	s_waitcnt lgkmcnt(0)
	v_pk_mul_f32 v[142:143], v[144:145], v[148:149]
	v_cndmask_b32_e64 v141, v141, -v141, s[6:7]
	v_cndmask_b32_e64 v140, v140, -v140, s[6:7]
	v_cndmask_b32_e64 v143, v143, -v143, s[6:7]
	v_cndmask_b32_e64 v142, v142, -v142, s[6:7]
	v_pk_fma_f32 v[76:77], v[76:77], v[150:151], v[140:141]
	v_pk_fma_f32 v[78:79], v[78:79], v[138:139], v[142:143]
.LBB0_309:
	s_or_b64 exec, exec, s[8:9]
	v_mov_b32_e32 v138, v134
	v_mov_b32_e32 v139, v134
	v_pk_mul_f32 v[140:141], v[138:139], v[78:79]
	v_pk_mul_f32 v[142:143], v[134:135], v[76:77]
	v_pk_mul_f32 v[144:145], v[134:135], v[72:73]
	v_cvt_pk_bf16_f32 v142, v142, v143
	v_cvt_pk_bf16_f32 v143, v140, v141
	v_pk_mul_f32 v[140:141], v[138:139], v[74:75]
	v_cvt_pk_bf16_f32 v144, v144, v145
	v_cvt_pk_bf16_f32 v145, v140, v141
	v_add_u32_e32 v128, 0x6000, v156
	ds_write2_b64 v128, v[142:143], v[144:145] offset0:96 offset1:100
	v_pk_mul_f32 v[140:141], v[138:139], v[70:71]
	v_pk_mul_f32 v[142:143], v[134:135], v[68:69]
	v_pk_mul_f32 v[144:145], v[134:135], v[64:65]
	v_cvt_pk_bf16_f32 v142, v142, v143
	v_cvt_pk_bf16_f32 v143, v140, v141
	v_pk_mul_f32 v[140:141], v[138:139], v[66:67]
	v_cvt_pk_bf16_f32 v144, v144, v145
	v_cvt_pk_bf16_f32 v145, v140, v141
	ds_write2_b64 v128, v[142:143], v[144:145] offset0:104 offset1:108
	s_and_saveexec_b64 s[8:9], s[46:47]
	s_cbranch_execz .LBB0_311
	v_or_b32_e32 v140, 64, v136
	v_ashrrev_i32_e32 v141, 31, v140
	v_lshlrev_b64 v[140:141], 6, v[140:141]
	v_lshl_add_u64 v[144:145], v[130:131], 0, v[140:141]
	s_nop 0
	v_and_b32_e32 v133, 64, v159
	v_xor_b32_e32 v128, 32, v159
	v_add_u32_e32 v133, 64, v133
	v_cmp_lt_i32_e32 vcc, v128, v133
	s_waitcnt vmcnt(7)
	v_mov_b32_e32 v140, v208
	v_mov_b32_e32 v141, v209
	v_mov_b32_e32 v142, v210
	v_mov_b32_e32 v143, v211
	v_mov_b32_e32 v161, v142
	v_cndmask_b32_e32 v128, v159, v128, vcc
	v_lshlrev_b32_e32 v128, 2, v128
	ds_bpermute_b32 v148, v128, v60
	ds_bpermute_b32 v149, v128, v61
	ds_bpermute_b32 v150, v128, v62
	ds_bpermute_b32 v151, v128, v63
	v_mov_b32_e32 v142, v141
	s_waitcnt vmcnt(6)
	v_mov_b32_e32 v144, v212
	v_mov_b32_e32 v145, v213
	v_mov_b32_e32 v146, v214
	v_mov_b32_e32 v147, v215
	v_mov_b32_e32 v141, v146
	v_mov_b32_e32 v146, v145
	v_mov_b32_e32 v160, v140
	v_mov_b32_e32 v140, v144
	s_waitcnt lgkmcnt(2)
	v_pk_mul_f32 v[142:143], v[142:143], v[148:149]
	s_waitcnt lgkmcnt(0)
	v_pk_mul_f32 v[144:145], v[146:147], v[150:151]
	v_cndmask_b32_e64 v143, v143, -v143, s[6:7]
	v_cndmask_b32_e64 v142, v142, -v142, s[6:7]
	v_cndmask_b32_e64 v145, v145, -v145, s[6:7]
	v_cndmask_b32_e64 v144, v144, -v144, s[6:7]
	v_pk_fma_f32 v[60:61], v[60:61], v[160:161], v[142:143]
	v_pk_fma_f32 v[62:63], v[62:63], v[140:141], v[144:145]
; __device__ void phaseC(const Params& p, char* lds) {
;     ...
; #pragma unroll
;         for (int mi = 0; mi < 8; mi++) {
;             const int tok = m0 + wr * 128 + mi * 16 + r;
;             if (rope) {
;                 f32x4 v = acc[mi][0];
;                 f32x4 pr;
; #pragma unroll
;                 for (int j = 0; j < 4; j++) pr[j] = __shfl_xor(v[j], 32, 64);
;                 const int ib = (q & 1) * 4;
;                 const f32x4 k0 = *(const f32x4*)(cs + (size_t)tok * 16 + ib * 2);
;                 const f32x4 k1 = *(const f32x4*)(cs + (size_t)tok * 16 + ib * 2 + 4);
;                 const float cc[4] = {k0[0], k0[2], k1[0], k1[2]}, sn[4] = {k0[1], k0[3], k1[1], k1[3]};
; #pragma unroll
;                 for (int j = 0; j < 4; j++) v[j] = (q < 2) ? (v[j] * cc[j] - pr[j] * sn[j]) : (v[j] * cc[j] + pr[j] * sn[j]);
;                 acc[mi][0] = v;
;             }
; #pragma unroll
;             for (int ni = 0; ni < 4; ni++) epi_fill(lds, wr, wc, r, q, mi, ni, acc[mi][ni] * scl);
.LBB0_311:
	s_or_b64 exec, exec, s[8:9]
	v_pk_mul_f32 v[140:141], v[138:139], v[62:63]
	v_pk_mul_f32 v[142:143], v[134:135], v[60:61]
	v_pk_mul_f32 v[144:145], v[134:135], v[56:57]
	v_cvt_pk_bf16_f32 v142, v142, v143
	v_cvt_pk_bf16_f32 v143, v140, v141
	v_pk_mul_f32 v[140:141], v[138:139], v[58:59]
	v_cvt_pk_bf16_f32 v144, v144, v145
	v_cvt_pk_bf16_f32 v145, v140, v141
	v_add_u32_e32 v128, 0x8000, v156
	ds_write2_b64 v128, v[142:143], v[144:145] offset0:128 offset1:132
	v_pk_mul_f32 v[140:141], v[138:139], v[54:55]
	v_pk_mul_f32 v[142:143], v[134:135], v[52:53]
	v_pk_mul_f32 v[138:139], v[138:139], v[50:51]
	v_cvt_pk_bf16_f32 v142, v142, v143
	v_cvt_pk_bf16_f32 v143, v140, v141
	v_pk_mul_f32 v[140:141], v[134:135], v[48:49]
	s_nop 0
	v_cvt_pk_bf16_f32 v140, v140, v141
	v_cvt_pk_bf16_f32 v141, v138, v139
	ds_write2_b64 v128, v[142:143], v[140:141] offset0:136 offset1:140
	s_and_saveexec_b64 s[8:9], s[46:47]
	s_cbranch_execz .LBB0_313
	v_or_b32_e32 v138, 0x50, v136
	v_ashrrev_i32_e32 v139, 31, v138
	v_lshlrev_b64 v[138:139], 6, v[138:139]
	v_lshl_add_u64 v[142:143], v[130:131], 0, v[138:139]
	s_nop 0
	v_and_b32_e32 v133, 64, v159
	v_xor_b32_e32 v128, 32, v159
	v_add_u32_e32 v133, 64, v133
	v_cmp_lt_i32_e32 vcc, v128, v133
	s_waitcnt vmcnt(5)
	v_mov_b32_e32 v138, v224
	v_mov_b32_e32 v139, v225
	v_mov_b32_e32 v140, v226
	v_mov_b32_e32 v141, v227
	v_mov_b32_e32 v151, v140
	v_cndmask_b32_e32 v128, v159, v128, vcc
	v_lshlrev_b32_e32 v128, 2, v128
	ds_bpermute_b32 v146, v128, v44
	ds_bpermute_b32 v147, v128, v45
	ds_bpermute_b32 v148, v128, v46
	ds_bpermute_b32 v149, v128, v47
	v_mov_b32_e32 v140, v139
	s_waitcnt vmcnt(4)
	v_mov_b32_e32 v142, v228
	v_mov_b32_e32 v143, v229
	v_mov_b32_e32 v144, v230
	v_mov_b32_e32 v145, v231
	v_mov_b32_e32 v139, v144
	v_mov_b32_e32 v144, v143
	v_mov_b32_e32 v150, v138
	v_mov_b32_e32 v138, v142
	s_waitcnt lgkmcnt(2)
	v_pk_mul_f32 v[140:141], v[140:141], v[146:147]
	s_waitcnt lgkmcnt(0)
	v_pk_mul_f32 v[142:143], v[144:145], v[148:149]
	v_cndmask_b32_e64 v141, v141, -v141, s[6:7]
	v_cndmask_b32_e64 v140, v140, -v140, s[6:7]
	v_cndmask_b32_e64 v143, v143, -v143, s[6:7]
	v_cndmask_b32_e64 v142, v142, -v142, s[6:7]
	v_pk_fma_f32 v[44:45], v[44:45], v[150:151], v[140:141]
	v_pk_fma_f32 v[46:47], v[46:47], v[138:139], v[142:143]
.LBB0_313:
	s_or_b64 exec, exec, s[8:9]
	v_mov_b32_e32 v138, v134
	v_mov_b32_e32 v139, v134
	v_pk_mul_f32 v[140:141], v[138:139], v[46:47]
	v_pk_mul_f32 v[142:143], v[134:135], v[44:45]
	v_pk_mul_f32 v[144:145], v[134:135], v[40:41]
	v_cvt_pk_bf16_f32 v142, v142, v143
	v_cvt_pk_bf16_f32 v143, v140, v141
	v_pk_mul_f32 v[140:141], v[138:139], v[42:43]
	v_cvt_pk_bf16_f32 v144, v144, v145
	v_cvt_pk_bf16_f32 v145, v140, v141
	v_add_u32_e32 v128, 0xa000, v156
	ds_write2_b64 v128, v[142:143], v[144:145] offset0:160 offset1:164
	v_pk_mul_f32 v[140:141], v[138:139], v[38:39]
	v_pk_mul_f32 v[142:143], v[134:135], v[36:37]
	v_pk_mul_f32 v[144:145], v[134:135], v[32:33]
	v_cvt_pk_bf16_f32 v142, v142, v143
	v_cvt_pk_bf16_f32 v143, v140, v141
	v_pk_mul_f32 v[140:141], v[138:139], v[34:35]
	v_cvt_pk_bf16_f32 v144, v144, v145
	v_cvt_pk_bf16_f32 v145, v140, v141
	ds_write2_b64 v128, v[142:143], v[144:145] offset0:168 offset1:172
	s_and_saveexec_b64 s[8:9], s[46:47]
	s_cbranch_execz .LBB0_315
	v_or_b32_e32 v140, 0x60, v136
	v_ashrrev_i32_e32 v141, 31, v140
	v_lshlrev_b64 v[140:141], 6, v[140:141]
	v_lshl_add_u64 v[144:145], v[130:131], 0, v[140:141]
	s_nop 0
	v_and_b32_e32 v133, 64, v159
	v_xor_b32_e32 v128, 32, v159
	v_add_u32_e32 v133, 64, v133
	v_cmp_lt_i32_e32 vcc, v128, v133
	s_waitcnt vmcnt(3)
	v_mov_b32_e32 v140, v232
	v_mov_b32_e32 v141, v233
	v_mov_b32_e32 v142, v234
	v_mov_b32_e32 v143, v235
	v_mov_b32_e32 v161, v142
	v_cndmask_b32_e32 v128, v159, v128, vcc
	v_lshlrev_b32_e32 v128, 2, v128
	ds_bpermute_b32 v148, v128, v28
	ds_bpermute_b32 v149, v128, v29
	ds_bpermute_b32 v150, v128, v30
	ds_bpermute_b32 v151, v128, v31
	v_mov_b32_e32 v142, v141
	s_waitcnt vmcnt(2)
	v_mov_b32_e32 v144, v236
	v_mov_b32_e32 v145, v237
	v_mov_b32_e32 v146, v238
	v_mov_b32_e32 v147, v239
	v_mov_b32_e32 v141, v146
	v_mov_b32_e32 v146, v145
	v_mov_b32_e32 v160, v140
	v_mov_b32_e32 v140, v144
	s_waitcnt lgkmcnt(2)
	v_pk_mul_f32 v[142:143], v[142:143], v[148:149]
	s_waitcnt lgkmcnt(0)
	v_pk_mul_f32 v[144:145], v[146:147], v[150:151]
	v_cndmask_b32_e64 v143, v143, -v143, s[6:7]
	v_cndmask_b32_e64 v142, v142, -v142, s[6:7]
	v_cndmask_b32_e64 v145, v145, -v145, s[6:7]
	v_cndmask_b32_e64 v144, v144, -v144, s[6:7]
	v_pk_fma_f32 v[28:29], v[28:29], v[160:161], v[142:143]
	v_pk_fma_f32 v[30:31], v[30:31], v[140:141], v[144:145]
.LBB0_315:
	s_or_b64 exec, exec, s[8:9]
	v_pk_mul_f32 v[140:141], v[138:139], v[30:31]
	v_pk_mul_f32 v[142:143], v[134:135], v[28:29]
	v_pk_mul_f32 v[144:145], v[134:135], v[24:25]
	v_cvt_pk_bf16_f32 v142, v142, v143
	v_cvt_pk_bf16_f32 v143, v140, v141
	v_pk_mul_f32 v[140:141], v[138:139], v[26:27]
	v_cvt_pk_bf16_f32 v144, v144, v145
	v_cvt_pk_bf16_f32 v145, v140, v141
	v_add_u32_e32 v128, 0xc000, v156
	ds_write2_b64 v128, v[142:143], v[144:145] offset0:192 offset1:196
	v_pk_mul_f32 v[140:141], v[138:139], v[22:23]
	v_pk_mul_f32 v[142:143], v[134:135], v[20:21]
	v_pk_mul_f32 v[138:139], v[138:139], v[18:19]
	v_cvt_pk_bf16_f32 v142, v142, v143
	v_cvt_pk_bf16_f32 v143, v140, v141
	v_pk_mul_f32 v[140:141], v[134:135], v[16:17]
	s_nop 0
	v_cvt_pk_bf16_f32 v140, v140, v141
	v_cvt_pk_bf16_f32 v141, v138, v139
	ds_write2_b64 v128, v[142:143], v[140:141] offset0:200 offset1:204
	s_and_saveexec_b64 s[8:9], s[46:47]
	s_cbranch_execz .LBB0_317
	v_or_b32_e32 v136, 0x70, v136
	v_ashrrev_i32_e32 v137, 31, v136
	v_lshlrev_b64 v[136:137], 6, v[136:137]
	v_lshl_add_u64 v[140:141], v[130:131], 0, v[136:137]
	s_nop 0
	v_and_b32_e32 v133, 64, v159
	v_xor_b32_e32 v128, 32, v159
	v_add_u32_e32 v133, 64, v133
	v_cmp_lt_i32_e32 vcc, v128, v133
	s_waitcnt vmcnt(1)
	v_mov_b32_e32 v136, v240
	v_mov_b32_e32 v137, v241
	v_mov_b32_e32 v138, v242
	v_mov_b32_e32 v139, v243
	v_mov_b32_e32 v149, v138
	v_cndmask_b32_e32 v128, v159, v128, vcc
	v_lshlrev_b32_e32 v128, 2, v128
	ds_bpermute_b32 v144, v128, v12
	ds_bpermute_b32 v145, v128, v13
	ds_bpermute_b32 v146, v128, v14
	ds_bpermute_b32 v147, v128, v15
	v_mov_b32_e32 v138, v137
	s_waitcnt vmcnt(0)
	v_mov_b32_e32 v140, v244
	v_mov_b32_e32 v141, v245
	v_mov_b32_e32 v142, v246
	v_mov_b32_e32 v143, v247
	v_mov_b32_e32 v137, v142
	v_mov_b32_e32 v142, v141
	v_mov_b32_e32 v148, v136
	v_mov_b32_e32 v136, v140
	s_waitcnt lgkmcnt(2)
	v_pk_mul_f32 v[138:139], v[138:139], v[144:145]
	s_waitcnt lgkmcnt(0)
	v_pk_mul_f32 v[140:141], v[142:143], v[146:147]
	v_cndmask_b32_e64 v139, v139, -v139, s[6:7]
	v_cndmask_b32_e64 v138, v138, -v138, s[6:7]
	v_cndmask_b32_e64 v141, v141, -v141, s[6:7]
	v_cndmask_b32_e64 v140, v140, -v140, s[6:7]
	v_pk_fma_f32 v[12:13], v[12:13], v[148:149], v[138:139]
	v_pk_fma_f32 v[14:15], v[14:15], v[136:137], v[140:141]
